# v64 + E2 epilogue q/k columns also staged through wave-private LDS and stored as 16-byte row chunks
# baseline (speedup 1.0000x reference)
.LBB0_862:
	s_or_b64 exec, exec, s[6:7]
	v_mov_b32_e32 v72, s9
	v_mov_b32_e32 v73, s11
	v_cndmask_b32_e32 v73, v72, v73, vcc
	v_mov_b32_e32 v72, s8
	v_mov_b32_e32 v74, s10
	v_cndmask_b32_e32 v72, v72, v74, vcc
	v_mov_b32_e32 v74, s19
	v_mov_b32_e32 v75, s25
	v_cndmask_b32_e32 v75, v74, v75, vcc
	v_mov_b32_e32 v74, s18
	v_mov_b32_e32 v78, s24
	v_ashrrev_i32_e32 v117, 31, v116
	v_cndmask_b32_e32 v74, v74, v78, vcc
	v_lshlrev_b64 v[78:79], 10, v[116:117]
	v_lshl_add_u64 v[74:75], v[74:75], 0, v[78:79]
	v_lshl_add_u64 v[92:93], v[108:109], 1, v[74:75]
	v_mul_f32_e32 v74, v105, v105
	v_pk_fma_f32 v[74:75], v[104:105], v[104:105], v[74:75] op_sel_hi:[1,1,0]
	v_mul_f32_e32 v78, v107, v107
	v_pk_fma_f32 v[74:75], v[106:107], v[106:107], v[74:75]
	s_mov_b32 s6, 0x800000
	v_pk_add_f32 v[74:75], v[78:79], v[74:75] op_sel_hi:[0,1]
	v_pk_fma_f32 v[74:75], v[100:101], v[100:101], v[74:75]
	v_mul_f32_e32 v78, v101, v101
	v_pk_add_f32 v[74:75], v[78:79], v[74:75] op_sel_hi:[0,1]
	v_pk_fma_f32 v[74:75], v[102:103], v[102:103], v[74:75]
	v_mul_f32_e32 v78, v103, v103
	v_pk_add_f32 v[74:75], v[78:79], v[74:75] op_sel_hi:[0,1]
	v_pk_fma_f32 v[74:75], v[96:97], v[96:97], v[74:75]
	v_mul_f32_e32 v78, v97, v97
	v_pk_add_f32 v[74:75], v[78:79], v[74:75] op_sel_hi:[0,1]
	v_pk_fma_f32 v[74:75], v[98:99], v[98:99], v[74:75]
	v_mul_f32_e32 v78, v99, v99
	v_pk_add_f32 v[74:75], v[78:79], v[74:75] op_sel_hi:[0,1]
	v_pk_fma_f32 v[74:75], v[88:89], v[88:89], v[74:75]
	v_mul_f32_e32 v78, v89, v89
	v_pk_add_f32 v[74:75], v[78:79], v[74:75] op_sel_hi:[0,1]
	v_pk_fma_f32 v[74:75], v[90:91], v[90:91], v[74:75]
	v_mul_f32_e32 v78, v91, v91
	v_pk_add_f32 v[74:75], v[78:79], v[74:75] op_sel_hi:[0,1]
	v_pk_fma_f32 v[74:75], v[84:85], v[84:85], v[74:75]
	v_mul_f32_e32 v78, v85, v85
	v_pk_add_f32 v[74:75], v[78:79], v[74:75] op_sel_hi:[0,1]
	v_pk_fma_f32 v[74:75], v[86:87], v[86:87], v[74:75]
	v_mul_f32_e32 v78, v87, v87
	v_pk_add_f32 v[74:75], v[78:79], v[74:75] op_sel_hi:[0,1]
	v_pk_fma_f32 v[74:75], v[80:81], v[80:81], v[74:75]
	v_mul_f32_e32 v78, v81, v81
	v_pk_add_f32 v[74:75], v[78:79], v[74:75] op_sel_hi:[0,1]
	v_pk_fma_f32 v[74:75], v[82:83], v[82:83], v[74:75]
	v_mul_f32_e32 v78, v83, v83
	v_pk_add_f32 v[74:75], v[78:79], v[74:75] op_sel_hi:[0,1]
	v_pk_fma_f32 v[74:75], v[68:69], v[68:69], v[74:75]
	v_mul_f32_e32 v78, v69, v69
	v_pk_add_f32 v[74:75], v[78:79], v[74:75] op_sel_hi:[0,1]
	v_pk_fma_f32 v[74:75], v[70:71], v[70:71], v[74:75]
	v_mul_f32_e32 v78, v71, v71
	v_pk_add_f32 v[74:75], v[78:79], v[74:75] op_sel_hi:[0,1]
	v_pk_fma_f32 v[74:75], v[64:65], v[64:65], v[74:75]
	v_mul_f32_e32 v78, v65, v65
	v_pk_add_f32 v[74:75], v[78:79], v[74:75] op_sel_hi:[0,1]
	v_pk_fma_f32 v[74:75], v[66:67], v[66:67], v[74:75]
	v_mul_f32_e32 v78, v67, v67
	v_pk_add_f32 v[74:75], v[78:79], v[74:75] op_sel_hi:[0,1]
	v_mov_b32_e32 v75, v74
	s_nop 1
	v_permlane32_swap_b32_e32 v74, v75
	v_add_f32_e32 v74, v74, v75
	v_fmamk_f32 v74, v74, 0x3c800000, v163
	v_cmp_gt_f32_e64 s[42:43], s6, v74
	v_mul_f32_e32 v75, 0x4b800000, v74
	v_lshlrev_b32_e32 v128, 2, v118
	v_cndmask_b32_e64 v74, v74, v75, s[42:43]
	v_rsq_f32_e32 v74, v74
	v_lshl_add_u64 v[94:95], v[72:73], 0, v[128:129]
	v_mul_f32_e32 v75, 0x45800000, v74
	v_cndmask_b32_e64 v78, v74, v75, s[42:43]
	global_load_dwordx4 v[198:201], v[94:95], off
	global_load_dwordx4 v[202:205], v[94:95], off offset:32
	global_load_dwordx4 v[206:209], v[94:95], off offset:64
	global_load_dwordx4 v[210:213], v[94:95], off offset:96
	global_load_dwordx4 v[214:217], v[94:95], off offset:128
	global_load_dwordx4 v[218:221], v[94:95], off offset:160
	global_load_dwordx4 v[222:225], v[94:95], off offset:192
	global_load_dwordx4 v[226:229], v[94:95], off offset:224
	v_pk_mul_f32 v[104:105], v[104:105], v[78:79] op_sel_hi:[1,0]
	v_cmp_ne_u64_e64 s[42:43], 0, v[76:77]
	s_waitcnt vmcnt(7)
	v_pk_mul_f32 v[72:73], v[198:199], v[104:105]
	v_pk_mul_f32 v[104:105], v[106:107], v[78:79] op_sel_hi:[1,0]
	s_nop 0
	v_pk_mul_f32 v[74:75], v[200:201], v[104:105]
	v_lshlrev_b32_e32 v104, 1, v118
	v_mov_b32_e32 v105, v129
	v_lshl_add_u64 v[92:93], v[92:93], 0, v[104:105]
	v_cvt_pk_bf16_f32 v104, v72, v73
	v_cvt_pk_bf16_f32 v105, v74, v75
	v_and_b32_e32 v240, 31, v155
	v_bfe_u32 v246, v155, 3, 3
	v_lshrrev_b32_e32 v239, 6, v155
	v_mul_u32_u24_e32 v239, 0x1400, v239
	v_mul_u32_u24_e32 v238, 0x90, v240
	v_mul_u32_u24_e32 v247, 0x90, v246
	v_add_u32_e32 v238, v238, v239
	v_add_u32_e32 v239, v247, v239
	v_sub_u32_e32 v247, v246, v240
	v_lshlrev_b32_e32 v247, 10, v247
	v_and_b32_e32 v246, 7, v155
	v_lshl_add_u32 v239, v246, 4, v239
	v_lshl_add_u32 v247, v246, 4, v247
	v_bfe_u32 v246, v155, 5, 1
	v_lshl_add_u32 v238, v246, 3, v238
	v_lshlrev_b32_e32 v246, 3, v246
	v_sub_u32_e32 v246, v247, v246
	v_ashrrev_i32_e32 v247, 31, v246
	v_lshl_add_u64 v[244:245], v[92:93], 0, v[246:247]
	v_mov_b32_e32 v246, 0x2000
	v_mov_b32_e32 v247, 0
	ds_write_b64 v238, v[104:105]
	s_and_saveexec_b64 s[6:7], s[42:43]
	s_cbranch_execz .LBB0_864
	v_lshl_add_u64 v[104:105], v[76:77], 0, v[128:129]
	global_store_dwordx4 v[104:105], v[72:75], off
.LBB0_864:
	s_or_b64 exec, exec, s[6:7]
	v_mov_b32_e32 v79, v78
	v_pk_mul_f32 v[100:101], v[100:101], v[78:79]
	v_pk_mul_f32 v[102:103], v[102:103], v[78:79]
	s_waitcnt vmcnt(6)
	v_pk_mul_f32 v[72:73], v[100:101], v[202:203]
	v_pk_mul_f32 v[74:75], v[102:103], v[204:205]
	v_cvt_pk_bf16_f32 v100, v72, v73
	v_cvt_pk_bf16_f32 v101, v74, v75
	ds_write_b64 v238, v[100:101] offset:16
	s_and_saveexec_b64 s[6:7], s[42:43]
	s_cbranch_execz .LBB0_866
	v_lshl_add_u64 v[100:101], v[76:77], 0, v[128:129]
	global_store_dwordx4 v[100:101], v[72:75], off offset:32
.LBB0_866:
	s_or_b64 exec, exec, s[6:7]
	v_pk_mul_f32 v[96:97], v[96:97], v[78:79]
	v_pk_mul_f32 v[98:99], v[98:99], v[78:79]
	s_waitcnt vmcnt(5)
	v_pk_mul_f32 v[72:73], v[96:97], v[206:207]
	v_pk_mul_f32 v[74:75], v[98:99], v[208:209]
	v_cvt_pk_bf16_f32 v96, v72, v73
	v_cvt_pk_bf16_f32 v97, v74, v75
	ds_write_b64 v238, v[96:97] offset:32
	s_and_saveexec_b64 s[6:7], s[42:43]
	s_cbranch_execz .LBB0_868
	v_lshl_add_u64 v[96:97], v[76:77], 0, v[128:129]
	global_store_dwordx4 v[96:97], v[72:75], off offset:64
.LBB0_868:
	s_or_b64 exec, exec, s[6:7]
	v_pk_mul_f32 v[88:89], v[88:89], v[78:79]
	v_pk_mul_f32 v[90:91], v[90:91], v[78:79]
	s_waitcnt vmcnt(4)
	v_pk_mul_f32 v[72:73], v[88:89], v[210:211]
	v_pk_mul_f32 v[74:75], v[90:91], v[212:213]
	v_cvt_pk_bf16_f32 v88, v72, v73
	v_cvt_pk_bf16_f32 v89, v74, v75
	ds_write_b64 v238, v[88:89] offset:48
	s_and_saveexec_b64 s[6:7], s[42:43]
	s_cbranch_execz .LBB0_870
	v_lshl_add_u64 v[88:89], v[76:77], 0, v[128:129]
	global_store_dwordx4 v[88:89], v[72:75], off offset:96
.LBB0_870:
	s_or_b64 exec, exec, s[6:7]
	v_pk_mul_f32 v[84:85], v[84:85], v[78:79]
	v_pk_mul_f32 v[86:87], v[86:87], v[78:79]
	s_waitcnt vmcnt(3)
	v_pk_mul_f32 v[72:73], v[84:85], v[214:215]
	v_pk_mul_f32 v[74:75], v[86:87], v[216:217]
	v_cvt_pk_bf16_f32 v84, v72, v73
	v_cvt_pk_bf16_f32 v85, v74, v75
	ds_write_b64 v238, v[84:85] offset:64
	s_and_saveexec_b64 s[6:7], s[42:43]
	s_cbranch_execz .LBB0_872
	v_lshl_add_u64 v[84:85], v[76:77], 0, v[128:129]
	global_store_dwordx4 v[84:85], v[72:75], off offset:128
.LBB0_872:
	s_or_b64 exec, exec, s[6:7]
	v_pk_mul_f32 v[80:81], v[80:81], v[78:79]
	v_pk_mul_f32 v[82:83], v[82:83], v[78:79]
	s_waitcnt vmcnt(2)
	v_pk_mul_f32 v[72:73], v[80:81], v[218:219]
	v_pk_mul_f32 v[74:75], v[82:83], v[220:221]
	v_cvt_pk_bf16_f32 v80, v72, v73
	v_cvt_pk_bf16_f32 v81, v74, v75
	ds_write_b64 v238, v[80:81] offset:80
	s_and_saveexec_b64 s[6:7], s[42:43]
	s_cbranch_execz .LBB0_874
	v_lshl_add_u64 v[80:81], v[76:77], 0, v[128:129]
	global_store_dwordx4 v[80:81], v[72:75], off offset:160
.LBB0_874:
	s_or_b64 exec, exec, s[6:7]
	v_pk_mul_f32 v[68:69], v[68:69], v[78:79]
	v_pk_mul_f32 v[70:71], v[70:71], v[78:79]
	s_waitcnt vmcnt(1)
	v_pk_mul_f32 v[68:69], v[68:69], v[222:223]
	v_pk_mul_f32 v[70:71], v[70:71], v[224:225]
	v_cvt_pk_bf16_f32 v72, v68, v69
	v_cvt_pk_bf16_f32 v73, v70, v71
	ds_write_b64 v238, v[72:73] offset:96
	s_and_saveexec_b64 s[6:7], s[42:43]
	s_cbranch_execz .LBB0_876
	v_lshl_add_u64 v[72:73], v[76:77], 0, v[128:129]
	global_store_dwordx4 v[72:73], v[68:71], off offset:192
.LBB0_876:
	s_or_b64 exec, exec, s[6:7]
	v_pk_mul_f32 v[64:65], v[64:65], v[78:79]
	v_pk_mul_f32 v[66:67], v[66:67], v[78:79]
	s_waitcnt vmcnt(0)
	v_pk_mul_f32 v[64:65], v[64:65], v[226:227]
	v_pk_mul_f32 v[66:67], v[66:67], v[228:229]
	v_cvt_pk_bf16_f32 v68, v64, v65
	v_cvt_pk_bf16_f32 v69, v66, v67
	ds_write_b64 v238, v[68:69] offset:112
	s_waitcnt lgkmcnt(0)
	ds_read_b128 v[230:233], v239 offset:0
	ds_read_b128 v[234:237], v239 offset:1152
	ds_read_b128 v[182:185], v239 offset:2304
	ds_read_b128 v[186:189], v239 offset:3456
	s_waitcnt lgkmcnt(3)
	global_store_dwordx4 v[244:245], v[230:233], off
	v_lshl_add_u64 v[244:245], v[244:245], 0, v[246:247]
	s_waitcnt lgkmcnt(2)
	global_store_dwordx4 v[244:245], v[234:237], off
	v_lshl_add_u64 v[244:245], v[244:245], 0, v[246:247]
	s_waitcnt lgkmcnt(1)
	global_store_dwordx4 v[244:245], v[182:185], off
	v_lshl_add_u64 v[244:245], v[244:245], 0, v[246:247]
	s_waitcnt lgkmcnt(0)
	global_store_dwordx4 v[244:245], v[186:189], off
	s_and_saveexec_b64 s[6:7], s[42:43]
	s_cbranch_execz .LBB0_878
	v_lshl_add_u64 v[68:69], v[76:77], 0, v[128:129]
	global_store_dwordx4 v[68:69], v[64:67], off offset:224

.LBB0_910:
	s_or_b64 exec, exec, s[6:7]
	v_mov_b32_e32 v40, s9
	v_mov_b32_e32 v41, s11
	v_cndmask_b32_e32 v41, v40, v41, vcc
	v_mov_b32_e32 v40, s8
	v_mov_b32_e32 v42, s10
	v_cndmask_b32_e32 v40, v40, v42, vcc
	v_mov_b32_e32 v42, s19
	v_mov_b32_e32 v43, s25
	v_cndmask_b32_e32 v43, v42, v43, vcc
	v_mov_b32_e32 v42, s18
	v_mov_b32_e32 v46, s24
	v_ashrrev_i32_e32 v79, 31, v78
	v_cndmask_b32_e32 v42, v42, v46, vcc
	v_lshlrev_b64 v[46:47], 10, v[78:79]
	v_lshl_add_u64 v[42:43], v[42:43], 0, v[46:47]
	v_lshl_add_u64 v[60:61], v[108:109], 1, v[42:43]
	v_mul_f32_e32 v42, v73, v73
	v_pk_fma_f32 v[42:43], v[72:73], v[72:73], v[42:43] op_sel_hi:[1,1,0]
	v_mul_f32_e32 v46, v75, v75
	v_pk_fma_f32 v[42:43], v[74:75], v[74:75], v[42:43]
	s_mov_b32 s6, 0x800000
	v_pk_add_f32 v[42:43], v[46:47], v[42:43] op_sel_hi:[0,1]
	v_pk_fma_f32 v[42:43], v[68:69], v[68:69], v[42:43]
	v_mul_f32_e32 v46, v69, v69
	v_pk_add_f32 v[42:43], v[46:47], v[42:43] op_sel_hi:[0,1]
	v_pk_fma_f32 v[42:43], v[70:71], v[70:71], v[42:43]
	v_mul_f32_e32 v46, v71, v71
	v_pk_add_f32 v[42:43], v[46:47], v[42:43] op_sel_hi:[0,1]
	v_pk_fma_f32 v[42:43], v[64:65], v[64:65], v[42:43]
	v_mul_f32_e32 v46, v65, v65
	v_pk_add_f32 v[42:43], v[46:47], v[42:43] op_sel_hi:[0,1]
	v_pk_fma_f32 v[42:43], v[66:67], v[66:67], v[42:43]
	v_mul_f32_e32 v46, v67, v67
	v_pk_add_f32 v[42:43], v[46:47], v[42:43] op_sel_hi:[0,1]
	v_pk_fma_f32 v[42:43], v[56:57], v[56:57], v[42:43]
	v_mul_f32_e32 v46, v57, v57
	v_pk_add_f32 v[42:43], v[46:47], v[42:43] op_sel_hi:[0,1]
	v_pk_fma_f32 v[42:43], v[58:59], v[58:59], v[42:43]
	v_mul_f32_e32 v46, v59, v59
	v_pk_add_f32 v[42:43], v[46:47], v[42:43] op_sel_hi:[0,1]
	v_pk_fma_f32 v[42:43], v[52:53], v[52:53], v[42:43]
	v_mul_f32_e32 v46, v53, v53
	v_pk_add_f32 v[42:43], v[46:47], v[42:43] op_sel_hi:[0,1]
	v_pk_fma_f32 v[42:43], v[54:55], v[54:55], v[42:43]
	v_mul_f32_e32 v46, v55, v55
	v_pk_add_f32 v[42:43], v[46:47], v[42:43] op_sel_hi:[0,1]
	v_pk_fma_f32 v[42:43], v[48:49], v[48:49], v[42:43]
	v_mul_f32_e32 v46, v49, v49
	v_pk_add_f32 v[42:43], v[46:47], v[42:43] op_sel_hi:[0,1]
	v_pk_fma_f32 v[42:43], v[50:51], v[50:51], v[42:43]
	v_mul_f32_e32 v46, v51, v51
	v_pk_add_f32 v[42:43], v[46:47], v[42:43] op_sel_hi:[0,1]
	v_pk_fma_f32 v[42:43], v[36:37], v[36:37], v[42:43]
	v_mul_f32_e32 v46, v37, v37
	v_pk_add_f32 v[42:43], v[46:47], v[42:43] op_sel_hi:[0,1]
	v_pk_fma_f32 v[42:43], v[38:39], v[38:39], v[42:43]
	v_mul_f32_e32 v46, v39, v39
	v_pk_add_f32 v[42:43], v[46:47], v[42:43] op_sel_hi:[0,1]
	v_pk_fma_f32 v[42:43], v[32:33], v[32:33], v[42:43]
	v_mul_f32_e32 v46, v33, v33
	v_pk_add_f32 v[42:43], v[46:47], v[42:43] op_sel_hi:[0,1]
	v_pk_fma_f32 v[42:43], v[34:35], v[34:35], v[42:43]
	v_mul_f32_e32 v46, v35, v35
	v_pk_add_f32 v[42:43], v[46:47], v[42:43] op_sel_hi:[0,1]
	v_mov_b32_e32 v43, v42
	s_nop 1
	v_permlane32_swap_b32_e32 v42, v43
	v_add_f32_e32 v42, v42, v43
	v_fmamk_f32 v42, v42, 0x3c800000, v163
	v_cmp_gt_f32_e64 s[42:43], s6, v42
	v_mul_f32_e32 v43, 0x4b800000, v42
	v_lshlrev_b32_e32 v128, 2, v118
	v_cndmask_b32_e64 v42, v42, v43, s[42:43]
	v_rsq_f32_e32 v42, v42
	v_lshl_add_u64 v[62:63], v[40:41], 0, v[128:129]
	v_mov_b32_e32 v77, v129
	v_lshl_add_u64 v[60:61], v[60:61], 0, v[76:77]
	v_mul_f32_e32 v43, 0x45800000, v42
	v_cndmask_b32_e64 v46, v42, v43, s[42:43]
	v_pk_mul_f32 v[72:73], v[72:73], v[46:47] op_sel_hi:[1,0]
	v_cmp_ne_u64_e64 s[42:43], 0, v[44:45]
	s_nop 0
	v_pk_mul_f32 v[40:41], v[198:199], v[72:73]
	v_pk_mul_f32 v[72:73], v[74:75], v[46:47] op_sel_hi:[1,0]
	s_nop 0
	v_pk_mul_f32 v[42:43], v[200:201], v[72:73]
	v_cvt_pk_bf16_f32 v72, v40, v41
	v_cvt_pk_bf16_f32 v73, v42, v43
	v_and_b32_e32 v240, 31, v155
	v_bfe_u32 v246, v155, 3, 3
	v_lshrrev_b32_e32 v239, 6, v155
	v_mul_u32_u24_e32 v239, 0x1400, v239
	v_mul_u32_u24_e32 v238, 0x90, v240
	v_mul_u32_u24_e32 v247, 0x90, v246
	v_add_u32_e32 v238, v238, v239
	v_add_u32_e32 v239, v247, v239
	v_sub_u32_e32 v247, v246, v240
	v_lshlrev_b32_e32 v247, 10, v247
	v_and_b32_e32 v246, 7, v155
	v_lshl_add_u32 v239, v246, 4, v239
	v_lshl_add_u32 v247, v246, 4, v247
	v_bfe_u32 v246, v155, 5, 1
	v_lshl_add_u32 v238, v246, 3, v238
	v_lshlrev_b32_e32 v246, 3, v246
	v_sub_u32_e32 v246, v247, v246
	v_ashrrev_i32_e32 v247, 31, v246
	v_lshl_add_u64 v[244:245], v[60:61], 0, v[246:247]
	v_mov_b32_e32 v246, 0x2000
	v_mov_b32_e32 v247, 0
	ds_write_b64 v238, v[72:73]
	s_and_saveexec_b64 s[6:7], s[42:43]
	s_cbranch_execz .LBB0_912
	v_lshl_add_u64 v[72:73], v[44:45], 0, v[128:129]
	global_store_dwordx4 v[72:73], v[40:43], off
.LBB0_912:
	s_or_b64 exec, exec, s[6:7]
	v_mov_b32_e32 v47, v46
	v_pk_mul_f32 v[68:69], v[68:69], v[46:47]
	v_pk_mul_f32 v[70:71], v[70:71], v[46:47]
	s_nop 0
	v_pk_mul_f32 v[40:41], v[68:69], v[202:203]
	v_pk_mul_f32 v[42:43], v[70:71], v[204:205]
	v_cvt_pk_bf16_f32 v68, v40, v41
	v_cvt_pk_bf16_f32 v69, v42, v43
	ds_write_b64 v238, v[68:69] offset:16
	s_and_saveexec_b64 s[6:7], s[42:43]
	s_cbranch_execz .LBB0_914
	v_lshl_add_u64 v[68:69], v[44:45], 0, v[128:129]
	global_store_dwordx4 v[68:69], v[40:43], off offset:32
.LBB0_914:
	s_or_b64 exec, exec, s[6:7]
	v_pk_mul_f32 v[64:65], v[64:65], v[46:47]
	v_pk_mul_f32 v[66:67], v[66:67], v[46:47]
	s_nop 0
	v_pk_mul_f32 v[40:41], v[64:65], v[206:207]
	v_pk_mul_f32 v[42:43], v[66:67], v[208:209]
	v_cvt_pk_bf16_f32 v64, v40, v41
	v_cvt_pk_bf16_f32 v65, v42, v43
	ds_write_b64 v238, v[64:65] offset:32
	s_and_saveexec_b64 s[6:7], s[42:43]
	s_cbranch_execz .LBB0_916
	v_lshl_add_u64 v[64:65], v[44:45], 0, v[128:129]
	global_store_dwordx4 v[64:65], v[40:43], off offset:64
.LBB0_916:
	s_or_b64 exec, exec, s[6:7]
	v_pk_mul_f32 v[56:57], v[56:57], v[46:47]
	v_pk_mul_f32 v[58:59], v[58:59], v[46:47]
	s_nop 0
	v_pk_mul_f32 v[40:41], v[56:57], v[210:211]
	v_pk_mul_f32 v[42:43], v[58:59], v[212:213]
	v_cvt_pk_bf16_f32 v56, v40, v41
	v_cvt_pk_bf16_f32 v57, v42, v43
	ds_write_b64 v238, v[56:57] offset:48
	s_and_saveexec_b64 s[6:7], s[42:43]
	s_cbranch_execz .LBB0_918
	v_lshl_add_u64 v[56:57], v[44:45], 0, v[128:129]
	global_store_dwordx4 v[56:57], v[40:43], off offset:96
.LBB0_918:
	s_or_b64 exec, exec, s[6:7]
	v_pk_mul_f32 v[52:53], v[52:53], v[46:47]
	v_pk_mul_f32 v[54:55], v[54:55], v[46:47]
	s_nop 0
	v_pk_mul_f32 v[40:41], v[52:53], v[214:215]
	v_pk_mul_f32 v[42:43], v[54:55], v[216:217]
	v_cvt_pk_bf16_f32 v52, v40, v41
	v_cvt_pk_bf16_f32 v53, v42, v43
	ds_write_b64 v238, v[52:53] offset:64
	s_and_saveexec_b64 s[6:7], s[42:43]
	s_cbranch_execz .LBB0_920
	v_lshl_add_u64 v[52:53], v[44:45], 0, v[128:129]
	global_store_dwordx4 v[52:53], v[40:43], off offset:128
.LBB0_920:
	s_or_b64 exec, exec, s[6:7]
	v_pk_mul_f32 v[48:49], v[48:49], v[46:47]
	v_pk_mul_f32 v[50:51], v[50:51], v[46:47]
	s_nop 0
	v_pk_mul_f32 v[40:41], v[48:49], v[218:219]
	v_pk_mul_f32 v[42:43], v[50:51], v[220:221]
	v_cvt_pk_bf16_f32 v48, v40, v41
	v_cvt_pk_bf16_f32 v49, v42, v43
	ds_write_b64 v238, v[48:49] offset:80
	s_and_saveexec_b64 s[6:7], s[42:43]
	s_cbranch_execz .LBB0_922
	v_lshl_add_u64 v[48:49], v[44:45], 0, v[128:129]
	global_store_dwordx4 v[48:49], v[40:43], off offset:160
.LBB0_922:
	s_or_b64 exec, exec, s[6:7]
	v_pk_mul_f32 v[36:37], v[36:37], v[46:47]
	v_pk_mul_f32 v[38:39], v[38:39], v[46:47]
	s_nop 0
	v_pk_mul_f32 v[36:37], v[36:37], v[222:223]
	v_pk_mul_f32 v[38:39], v[38:39], v[224:225]
	v_cvt_pk_bf16_f32 v40, v36, v37
	v_cvt_pk_bf16_f32 v41, v38, v39
	ds_write_b64 v238, v[40:41] offset:96
	s_and_saveexec_b64 s[6:7], s[42:43]
	s_cbranch_execz .LBB0_924
	v_lshl_add_u64 v[40:41], v[44:45], 0, v[128:129]
	global_store_dwordx4 v[40:41], v[36:39], off offset:192
.LBB0_924:
	s_or_b64 exec, exec, s[6:7]
	v_pk_mul_f32 v[32:33], v[32:33], v[46:47]
	v_pk_mul_f32 v[34:35], v[34:35], v[46:47]
	s_nop 0
	v_pk_mul_f32 v[32:33], v[32:33], v[226:227]
	v_pk_mul_f32 v[34:35], v[34:35], v[228:229]
	v_cvt_pk_bf16_f32 v36, v32, v33
	v_cvt_pk_bf16_f32 v37, v34, v35
	ds_write_b64 v238, v[36:37] offset:112
	s_waitcnt lgkmcnt(0)
	ds_read_b128 v[230:233], v239 offset:0
	ds_read_b128 v[234:237], v239 offset:1152
	ds_read_b128 v[182:185], v239 offset:2304
	ds_read_b128 v[186:189], v239 offset:3456
	s_waitcnt lgkmcnt(3)
	global_store_dwordx4 v[244:245], v[230:233], off
	v_lshl_add_u64 v[244:245], v[244:245], 0, v[246:247]
	s_waitcnt lgkmcnt(2)
	global_store_dwordx4 v[244:245], v[234:237], off
	v_lshl_add_u64 v[244:245], v[244:245], 0, v[246:247]
	s_waitcnt lgkmcnt(1)
	global_store_dwordx4 v[244:245], v[182:185], off
	v_lshl_add_u64 v[244:245], v[244:245], 0, v[246:247]
	s_waitcnt lgkmcnt(0)
	global_store_dwordx4 v[244:245], v[186:189], off
	s_and_saveexec_b64 s[6:7], s[42:43]
	s_cbranch_execz .LBB0_926
	v_lshl_add_u64 v[36:37], v[44:45], 0, v[128:129]
	global_store_dwordx4 v[36:37], v[32:35], off offset:224

.LBB0_958:
	s_or_b64 exec, exec, s[4:5]
	v_mov_b32_e32 v16, s9
	v_mov_b32_e32 v17, s11
	v_cndmask_b32_e32 v17, v16, v17, vcc
	v_mov_b32_e32 v16, s8
	v_mov_b32_e32 v18, s10
	v_cndmask_b32_e32 v16, v16, v18, vcc
	v_mov_b32_e32 v18, s19
	v_mov_b32_e32 v19, s25
	v_cndmask_b32_e32 v19, v18, v19, vcc
	v_mov_b32_e32 v18, s18
	v_mov_b32_e32 v22, s24
	v_ashrrev_i32_e32 v49, 31, v48
	v_cndmask_b32_e32 v18, v18, v22, vcc
	v_lshlrev_b64 v[22:23], 10, v[48:49]
	v_lshl_add_u64 v[18:19], v[18:19], 0, v[22:23]
	v_lshl_add_u64 v[24:25], v[108:109], 1, v[18:19]
	v_mul_f32_e32 v18, v45, v45
	v_pk_fma_f32 v[18:19], v[44:45], v[44:45], v[18:19] op_sel_hi:[1,1,0]
	v_mul_f32_e32 v22, v47, v47
	v_pk_fma_f32 v[18:19], v[46:47], v[46:47], v[18:19]
	s_mov_b32 s4, 0x800000
	v_pk_add_f32 v[18:19], v[22:23], v[18:19] op_sel_hi:[0,1]
	v_pk_fma_f32 v[18:19], v[40:41], v[40:41], v[18:19]
	v_mul_f32_e32 v22, v41, v41
	v_pk_add_f32 v[18:19], v[22:23], v[18:19] op_sel_hi:[0,1]
	v_pk_fma_f32 v[18:19], v[42:43], v[42:43], v[18:19]
	v_mul_f32_e32 v22, v43, v43
	v_pk_add_f32 v[18:19], v[22:23], v[18:19] op_sel_hi:[0,1]
	v_pk_fma_f32 v[18:19], v[36:37], v[36:37], v[18:19]
	v_mul_f32_e32 v22, v37, v37
	v_pk_add_f32 v[18:19], v[22:23], v[18:19] op_sel_hi:[0,1]
	v_pk_fma_f32 v[18:19], v[38:39], v[38:39], v[18:19]
	v_mul_f32_e32 v22, v39, v39
	v_pk_add_f32 v[18:19], v[22:23], v[18:19] op_sel_hi:[0,1]
	v_pk_fma_f32 v[18:19], v[32:33], v[32:33], v[18:19]
	v_mul_f32_e32 v22, v33, v33
	v_pk_add_f32 v[18:19], v[22:23], v[18:19] op_sel_hi:[0,1]
	v_pk_fma_f32 v[18:19], v[34:35], v[34:35], v[18:19]
	v_mul_f32_e32 v22, v35, v35
	v_pk_add_f32 v[18:19], v[22:23], v[18:19] op_sel_hi:[0,1]
	v_pk_fma_f32 v[18:19], v[12:13], v[12:13], v[18:19]
	v_mul_f32_e32 v22, v13, v13
	v_pk_add_f32 v[18:19], v[22:23], v[18:19] op_sel_hi:[0,1]
	v_pk_fma_f32 v[18:19], v[14:15], v[14:15], v[18:19]
	v_mul_f32_e32 v22, v15, v15
	v_pk_add_f32 v[18:19], v[22:23], v[18:19] op_sel_hi:[0,1]
	v_pk_fma_f32 v[18:19], v[8:9], v[8:9], v[18:19]
	v_mul_f32_e32 v22, v9, v9
	v_pk_add_f32 v[18:19], v[22:23], v[18:19] op_sel_hi:[0,1]
	v_pk_fma_f32 v[18:19], v[10:11], v[10:11], v[18:19]
	v_mul_f32_e32 v22, v11, v11
	v_pk_add_f32 v[18:19], v[22:23], v[18:19] op_sel_hi:[0,1]
	v_pk_fma_f32 v[18:19], v[4:5], v[4:5], v[18:19]
	v_mul_f32_e32 v22, v5, v5
	v_pk_add_f32 v[18:19], v[22:23], v[18:19] op_sel_hi:[0,1]
	v_pk_fma_f32 v[18:19], v[6:7], v[6:7], v[18:19]
	v_mul_f32_e32 v22, v7, v7
	v_pk_add_f32 v[18:19], v[22:23], v[18:19] op_sel_hi:[0,1]
	v_pk_fma_f32 v[18:19], v[0:1], v[0:1], v[18:19]
	v_mul_f32_e32 v22, v1, v1
	v_pk_add_f32 v[18:19], v[22:23], v[18:19] op_sel_hi:[0,1]
	v_pk_fma_f32 v[18:19], v[2:3], v[2:3], v[18:19]
	v_mul_f32_e32 v22, v3, v3
	v_pk_add_f32 v[18:19], v[22:23], v[18:19] op_sel_hi:[0,1]
	v_mov_b32_e32 v19, v18
	s_nop 1
	v_permlane32_swap_b32_e32 v18, v19
	v_add_f32_e32 v18, v18, v19
	v_fmamk_f32 v18, v18, 0x3c800000, v163
	v_cmp_gt_f32_e32 vcc, s4, v18
	v_mul_f32_e32 v19, 0x4b800000, v18
	v_lshlrev_b32_e32 v128, 2, v118
	v_cndmask_b32_e32 v18, v18, v19, vcc
	v_rsq_f32_e32 v18, v18
	v_lshl_add_u64 v[26:27], v[16:17], 0, v[128:129]
	v_mov_b32_e32 v77, v129
	v_lshl_add_u64 v[24:25], v[24:25], 0, v[76:77]
	v_mul_f32_e32 v19, 0x45800000, v18
	v_cndmask_b32_e32 v22, v18, v19, vcc
	v_pk_mul_f32 v[28:29], v[44:45], v[22:23] op_sel_hi:[1,0]
	v_cmp_ne_u64_e32 vcc, 0, v[20:21]
	s_nop 0
	v_pk_mul_f32 v[16:17], v[198:199], v[28:29]
	v_pk_mul_f32 v[28:29], v[46:47], v[22:23] op_sel_hi:[1,0]
	s_nop 0
	v_pk_mul_f32 v[18:19], v[200:201], v[28:29]
	v_cvt_pk_bf16_f32 v28, v16, v17
	v_cvt_pk_bf16_f32 v29, v18, v19
	v_and_b32_e32 v240, 31, v155
	v_bfe_u32 v246, v155, 3, 3
	v_lshrrev_b32_e32 v239, 6, v155
	v_mul_u32_u24_e32 v239, 0x1400, v239
	v_mul_u32_u24_e32 v238, 0x90, v240
	v_mul_u32_u24_e32 v247, 0x90, v246
	v_add_u32_e32 v238, v238, v239
	v_add_u32_e32 v239, v247, v239
	v_sub_u32_e32 v247, v246, v240
	v_lshlrev_b32_e32 v247, 10, v247
	v_and_b32_e32 v246, 7, v155
	v_lshl_add_u32 v239, v246, 4, v239
	v_lshl_add_u32 v247, v246, 4, v247
	v_bfe_u32 v246, v155, 5, 1
	v_lshl_add_u32 v238, v246, 3, v238
	v_lshlrev_b32_e32 v246, 3, v246
	v_sub_u32_e32 v246, v247, v246
	v_ashrrev_i32_e32 v247, 31, v246
	v_lshl_add_u64 v[244:245], v[24:25], 0, v[246:247]
	v_mov_b32_e32 v246, 0x2000
	v_mov_b32_e32 v247, 0
	ds_write_b64 v238, v[28:29]
	s_and_saveexec_b64 s[4:5], vcc
	s_cbranch_execz .LBB0_960
	v_lshl_add_u64 v[28:29], v[20:21], 0, v[128:129]
	global_store_dwordx4 v[28:29], v[16:19], off
.LBB0_960:
	s_or_b64 exec, exec, s[4:5]
	v_mov_b32_e32 v23, v22
	v_pk_mul_f32 v[28:29], v[40:41], v[22:23]
	v_pk_mul_f32 v[30:31], v[42:43], v[22:23]
	s_nop 0
	v_pk_mul_f32 v[16:17], v[28:29], v[202:203]
	v_pk_mul_f32 v[18:19], v[30:31], v[204:205]
	v_cvt_pk_bf16_f32 v28, v16, v17
	v_cvt_pk_bf16_f32 v29, v18, v19
	ds_write_b64 v238, v[28:29] offset:16
	s_and_saveexec_b64 s[4:5], vcc
	s_cbranch_execz .LBB0_962
	v_lshl_add_u64 v[28:29], v[20:21], 0, v[128:129]
	global_store_dwordx4 v[28:29], v[16:19], off offset:32
.LBB0_962:
	s_or_b64 exec, exec, s[4:5]
	v_pk_mul_f32 v[28:29], v[36:37], v[22:23]
	v_pk_mul_f32 v[30:31], v[38:39], v[22:23]
	s_nop 0
	v_pk_mul_f32 v[16:17], v[28:29], v[206:207]
	v_pk_mul_f32 v[18:19], v[30:31], v[208:209]
	v_cvt_pk_bf16_f32 v28, v16, v17
	v_cvt_pk_bf16_f32 v29, v18, v19
	ds_write_b64 v238, v[28:29] offset:32
	s_and_saveexec_b64 s[4:5], vcc
	s_cbranch_execz .LBB0_964
	v_lshl_add_u64 v[28:29], v[20:21], 0, v[128:129]
	global_store_dwordx4 v[28:29], v[16:19], off offset:64
.LBB0_964:
	s_or_b64 exec, exec, s[4:5]
	v_pk_mul_f32 v[28:29], v[32:33], v[22:23]
	v_pk_mul_f32 v[30:31], v[34:35], v[22:23]
	s_nop 0
	v_pk_mul_f32 v[16:17], v[28:29], v[210:211]
	v_pk_mul_f32 v[18:19], v[30:31], v[212:213]
	v_cvt_pk_bf16_f32 v28, v16, v17
	v_cvt_pk_bf16_f32 v29, v18, v19
	ds_write_b64 v238, v[28:29] offset:48
	s_and_saveexec_b64 s[4:5], vcc
	s_cbranch_execz .LBB0_966
	v_lshl_add_u64 v[28:29], v[20:21], 0, v[128:129]
	global_store_dwordx4 v[28:29], v[16:19], off offset:96
.LBB0_966:
	s_or_b64 exec, exec, s[4:5]
	v_pk_mul_f32 v[12:13], v[12:13], v[22:23]
	v_pk_mul_f32 v[14:15], v[14:15], v[22:23]
	s_nop 0
	v_pk_mul_f32 v[12:13], v[12:13], v[214:215]
	v_pk_mul_f32 v[14:15], v[14:15], v[216:217]
	v_cvt_pk_bf16_f32 v16, v12, v13
	v_cvt_pk_bf16_f32 v17, v14, v15
	ds_write_b64 v238, v[16:17] offset:64
	s_and_saveexec_b64 s[4:5], vcc
	s_cbranch_execz .LBB0_968
	v_lshl_add_u64 v[16:17], v[20:21], 0, v[128:129]
	global_store_dwordx4 v[16:17], v[12:15], off offset:128
.LBB0_968:
	s_or_b64 exec, exec, s[4:5]
	v_pk_mul_f32 v[8:9], v[8:9], v[22:23]
	v_pk_mul_f32 v[10:11], v[10:11], v[22:23]
	s_nop 0
	v_pk_mul_f32 v[8:9], v[8:9], v[218:219]
	v_pk_mul_f32 v[10:11], v[10:11], v[220:221]
	v_cvt_pk_bf16_f32 v12, v8, v9
	v_cvt_pk_bf16_f32 v13, v10, v11
	ds_write_b64 v238, v[12:13] offset:80
	s_and_saveexec_b64 s[4:5], vcc
	s_cbranch_execz .LBB0_970
	v_lshl_add_u64 v[12:13], v[20:21], 0, v[128:129]
	global_store_dwordx4 v[12:13], v[8:11], off offset:160
.LBB0_970:
	s_or_b64 exec, exec, s[4:5]
	v_pk_mul_f32 v[4:5], v[4:5], v[22:23]
	v_pk_mul_f32 v[6:7], v[6:7], v[22:23]
	s_nop 0
	v_pk_mul_f32 v[4:5], v[4:5], v[222:223]
	v_pk_mul_f32 v[6:7], v[6:7], v[224:225]
	v_cvt_pk_bf16_f32 v8, v4, v5
	v_cvt_pk_bf16_f32 v9, v6, v7
	ds_write_b64 v238, v[8:9] offset:96
	s_and_saveexec_b64 s[4:5], vcc
	s_cbranch_execz .LBB0_972
	v_lshl_add_u64 v[8:9], v[20:21], 0, v[128:129]
	global_store_dwordx4 v[8:9], v[4:7], off offset:192
.LBB0_972:
	s_or_b64 exec, exec, s[4:5]
	v_pk_mul_f32 v[0:1], v[0:1], v[22:23]
	v_pk_mul_f32 v[2:3], v[2:3], v[22:23]
	s_nop 0
	v_pk_mul_f32 v[0:1], v[0:1], v[226:227]
	v_pk_mul_f32 v[2:3], v[2:3], v[228:229]
	v_cvt_pk_bf16_f32 v4, v0, v1
	v_cvt_pk_bf16_f32 v5, v2, v3
	ds_write_b64 v238, v[4:5] offset:112
	s_waitcnt lgkmcnt(0)
	ds_read_b128 v[230:233], v239 offset:0
	ds_read_b128 v[234:237], v239 offset:1152
	ds_read_b128 v[182:185], v239 offset:2304
	ds_read_b128 v[186:189], v239 offset:3456
	s_waitcnt lgkmcnt(3)
	global_store_dwordx4 v[244:245], v[230:233], off
	v_lshl_add_u64 v[244:245], v[244:245], 0, v[246:247]
	s_waitcnt lgkmcnt(2)
	global_store_dwordx4 v[244:245], v[234:237], off
	v_lshl_add_u64 v[244:245], v[244:245], 0, v[246:247]
	s_waitcnt lgkmcnt(1)
	global_store_dwordx4 v[244:245], v[182:185], off
	v_lshl_add_u64 v[244:245], v[244:245], 0, v[246:247]
	s_waitcnt lgkmcnt(0)
	global_store_dwordx4 v[244:245], v[186:189], off
	s_and_saveexec_b64 s[4:5], vcc
	s_cbranch_execz .LBB0_974
	v_lshl_add_u64 v[4:5], v[20:21], 0, v[128:129]
	global_store_dwordx4 v[4:5], v[0:3], off offset:224
